# attention B-items: query loads hoisted above K/V staging (on top of P0 fast path with nt loads)
# speedup vs baseline: 1.0027x; 1.0027x over previous
; #define LAS __attribute__((address_space(3)))
; __global__ void __launch_bounds__(512, 2) hybrid_fwd(Args a) {
;     ...
;                 const int bi = it - N_A, grp = bi >> 9, rem = bi & 511, hs = rem >> 7, rb = rem & 127;
;                 const int dsh = 2 * grp, d = 1 << dsh;
;                 const int nblk = 128 >> dsh, r = rb / nblk, b = rb % nblk;
;                 LAS unsigned char* Kl = lds; LAS unsigned char* Vl = lds + 256 * 288;
;                 const int jlo = (b == 0) ? 128 : 0;
;                 const int colh = grp * 512 + hs * 128;
;                 load_kv<128>(Kl, Vl, H + OFF_KB + colh, H + OFF_VB + colh, ((long)(b - 1) * 128) * d + r, d, jlo, tid);
;                 __syncthreads();
;                 const size_t tok = ((size_t)b * 128 + wave * 16 + (lane & 15)) * d + r;
;                 const bf16_t* qrow = H + tok * DIN + OFF_QB + colh;
;                 bf16x8 qb4[4]; u32x2 gdum[8];
; #pragma unroll
;                 for (int ks = 0; ks < 4; ++ks) qb4[ks] = *(const bf16x8*)(qrow + ks * 32 + 8 * (lane >> 4));
.LBB0_310:
	s_or_b64 exec, exec, s[14:15]
	s_movk_i32 s14, 0xff
	v_cmp_lt_i32_e32 vcc, s14, v1
	s_barrier
	s_and_saveexec_b64 s[14:15], vcc
	s_xor_b64 s[86:87], exec, s[14:15]
	s_cbranch_execz .LBB0_328
	v_add_u32_e32 v2, 0xffffff00, v1
	v_lshrrev_b32_e32 v148, 9, v2
	v_lshlrev_b32_e32 v147, 1, v148
	s_movk_i32 s14, 0x80
	v_and_b32_e32 v0, 0x7f, v1
	v_lshrrev_b32_e64 v3, v147, s14
	v_sub_u32_e32 v4, 7, v147
	v_lshrrev_b32_e32 v154, v4, v0
	v_add_u32_e32 v0, -1, v3
	s_movk_i32 s14, 0x7f
	v_bitop3_b32 v149, v0, v1, s14 bitop3:0x80
	v_bfe_u32 v222, v2, 7, 2
	v_subrev_co_u32_e32 v0, vcc, 1, v149
	v_lshlrev_b32_e32 v150, 7, v222
	s_movk_i32 s14, 0xfe00
	v_ashrrev_i32_e32 v1, 31, v0
	v_and_or_b32 v152, v2, s14, v150
	v_mov_b32_e32 v153, v8
	v_lshlrev_b64 v[0:1], 7, v[0:1]
	v_lshl_add_u32 v232, v149, 7, v174
	v_lshlrev_b32_e32 v232, v147, v232
	v_add_u32_e32 v232, v232, v154
	v_mov_b64_e32 v[234:235], s[96:97]
	v_mad_u64_u32 v[234:235], s[100:101], v232, s20, v[234:235]
	v_mov_b32_e32 v240, v146
	v_mov_b32_e32 v241, 0
	v_lshl_add_u64 v[234:235], v[152:153], 1, v[234:235]
	v_lshl_add_u64 v[234:235], v[234:235], 0, v[240:241]
	s_mov_b64 s[100:101], 0x1200
	v_lshl_add_u64 v[234:235], v[234:235], 0, s[100:101]
	global_load_dwordx4 v[244:247], v[234:235], off
	global_load_dwordx4 v[248:251], v[234:235], off offset:64
	global_load_dwordx4 v[252:255], v[234:235], off offset:128
	global_load_dwordx4 v[236:239], v[234:235], off offset:192
	v_mov_b32_e32 v96, 0
	v_cndmask_b32_e32 v223, 0, v219, vcc
	v_lshlrev_b64 v[2:3], 1, v[152:153]
	v_lshlrev_b64 v[166:167], v147, v[0:1]
	v_lshl_add_u64 v[158:159], s[4:5], 0, v[2:3]
	v_lshl_add_u64 v[164:165], s[8:9], 0, v[2:3]
	v_or_b32_e32 v166, v166, v154
	v_cmp_ge_u32_e32 vcc, v112, v223
	v_mov_b32_e32 v97, v96
	v_mov_b32_e32 v98, v96
	v_mov_b32_e32 v99, v96
	v_mov_b32_e32 v0, v96
	v_mov_b32_e32 v1, v96
	v_mov_b32_e32 v2, v96
	v_mov_b32_e32 v3, v96
	s_and_saveexec_b64 s[14:15], vcc
	s_cbranch_execz .LBB0_313
	v_lshlrev_b64 v[0:1], v147, v[112:113]
	v_lshl_add_u64 v[0:1], v[166:167], 0, v[0:1]
	v_mad_u64_u32 v[2:3], s[16:17], v0, s19, 0
	v_mov_b32_e32 v0, v3
	v_mad_u64_u32 v[0:1], s[16:17], v1, s19, v[0:1]
	v_or_b32_e32 v2, v2, v110
	v_mov_b32_e32 v3, v0
	v_lshlrev_b64 v[0:1], 1, v[2:3]
	v_lshl_add_u64 v[2:3], v[158:159], 0, v[0:1]
	v_lshl_add_u64 v[4:5], v[164:165], 0, v[0:1]
	global_load_dwordx4 v[0:3], v[2:3], off
	s_nop 0
	global_load_dwordx4 v[96:99], v[4:5], off

; #define LAS __attribute__((address_space(3)))
; template <int DH, bool IS_A> ...
;     ...
; #pragma unroll
;     for (int T = 0; T < 9; ++T) { s[T] = (f32x4){0.f, 0.f, 0.f, 0.f}; kf[0][T] = *(const LAS bf16x8*)(kp + T * 16 * KS); }
; #pragma unroll
;     for (int ks = 0; ks < NKS; ++ks) {
;         if (ks + 1 < NKS) {
; #pragma unroll
;             for (int T = 0; T < 9; ++T) kf[(ks + 1) & 1][T] = *(const LAS bf16x8*)(kp + T * 16 * KS + (ks + 1) * 64); }
;         __builtin_amdgcn_sched_barrier(0);
; #pragma unroll
;         for (int T = 0; T < 9; ++T) s[T] = __builtin_amdgcn_mfma_f32_16x16x32_bf16(kf[ks & 1][T], qf[ks], s[T], 0, 0, 0);
; template <int DH>
; __device__ __forceinline__ void load_kv(LAS unsigned char* Kl, LAS unsigned char* Vl, const bf16_t* Hk, const bf16_t* Hv, long tok0, int tstride, int jlo, int tid) {
;     ...
;     for (int c = 0; c < PER; ++c) { const int idx = c * 512 + tid, row = idx / CPR, ch = idx % CPR;
;         *(LAS u32x4*)(Kl + row * KS + ch * 16) = kv[c]; *(LAS u32x4*)(Vl + row * VS + ch * 16) = vv[c]; }
.LBB0_325:
	s_or_b64 exec, exec, s[14:15]
	v_lshlrev_b64 v[4:5], v147, v[120:121]
	v_lshlrev_b64 v[14:15], v147, v[122:123]
	v_lshl_add_u64 v[4:5], v[166:167], 0, v[4:5]
	v_lshl_add_u64 v[14:15], v[166:167], 0, v[14:15]
	v_mad_u64_u32 v[6:7], s[14:15], v4, s19, 0
	v_mad_u64_u32 v[16:17], s[14:15], v14, s19, 0
	v_lshlrev_b64 v[22:23], v147, v[124:125]
	v_lshlrev_b64 v[30:31], v147, v[126:127]
	v_mov_b32_e32 v4, v7
	v_mov_b32_e32 v14, v17
	v_lshl_add_u64 v[22:23], v[166:167], 0, v[22:23]
	v_lshl_add_u64 v[30:31], v[166:167], 0, v[30:31]
	v_mad_u64_u32 v[4:5], s[14:15], v5, s19, v[4:5]
	v_mad_u64_u32 v[14:15], s[14:15], v15, s19, v[14:15]
	v_mad_u64_u32 v[24:25], s[14:15], v22, s19, 0
	v_mad_u64_u32 v[48:49], s[14:15], v30, s19, 0
	v_or_b32_e32 v6, v6, v110
	v_mov_b32_e32 v7, v4
	v_or_b32_e32 v16, v16, v110
	v_mov_b32_e32 v17, v14
	v_mov_b32_e32 v22, v25
	v_mov_b32_e32 v30, v49
	v_lshlrev_b64 v[10:11], 1, v[6:7]
	v_lshlrev_b64 v[18:19], 1, v[16:17]
	v_mad_u64_u32 v[22:23], s[14:15], v23, s19, v[22:23]
	v_mad_u64_u32 v[30:31], s[14:15], v31, s19, v[30:31]
	v_lshl_add_u64 v[4:5], v[158:159], 0, v[10:11]
	v_lshl_add_u64 v[14:15], v[158:159], 0, v[18:19]
	v_or_b32_e32 v24, v24, v110
	v_mov_b32_e32 v25, v22
	v_or_b32_e32 v48, v48, v110
	v_mov_b32_e32 v49, v30
	global_load_dwordx4 v[4:7], v[4:5], off
	v_lshl_add_u64 v[10:11], v[164:165], 0, v[10:11]
	global_load_dwordx4 v[14:17], v[14:15], off
	v_lshl_add_u64 v[18:19], v[164:165], 0, v[18:19]
	v_lshlrev_b64 v[26:27], 1, v[24:25]
	v_lshlrev_b64 v[30:31], 1, v[48:49]
	global_load_dwordx4 v[10:13], v[10:11], off
	v_lshl_add_u64 v[22:23], v[158:159], 0, v[26:27]
	global_load_dwordx4 v[18:21], v[18:19], off
	v_lshl_add_u64 v[48:49], v[164:165], 0, v[30:31]
	v_lshl_add_u64 v[30:31], v[158:159], 0, v[30:31]
	global_load_dwordx4 v[22:25], v[22:23], off
	v_lshl_add_u64 v[26:27], v[164:165], 0, v[26:27]
	global_load_dwordx4 v[48:51], v[48:49], off
	v_add_u32_e32 v9, v163, v169
	global_load_dwordx4 v[52:55], v[30:31], off
	v_add_u32_e32 v30, v168, v169
	global_load_dwordx4 v[26:29], v[26:27], off
	v_add_u32_e32 v31, v163, v170
	ds_write_b128 v9, v[32:35]
	s_waitcnt vmcnt(8)
	ds_write_b128 v30, v[96:99]
	ds_write_b128 v31, v[36:39]
	v_add_u32_e32 v31, v168, v170
	ds_write_b128 v31, v[100:103]
	ds_write_b128 v9, v[40:43] offset:18432
	ds_write_b128 v30, v[104:107] offset:18432
	v_add_u32_e32 v31, v163, v171
	ds_write_b128 v31, v[44:47]
	v_add_u32_e32 v31, v168, v171
	v_mov_b32_e32 v155, v8
	v_mov_b32_e32 v151, v8
	ds_write_b128 v31, v[0:3]
	s_waitcnt vmcnt(7)
	ds_write_b128 v9, v[4:7] offset:36864
	s_waitcnt vmcnt(5)
	ds_write_b128 v30, v[10:13] offset:36864
	v_add_u32_e32 v0, v163, v172
	ds_write_b128 v0, v[14:17]
	v_add_u32_e32 v0, v168, v172
	s_waitcnt vmcnt(4)
	ds_write_b128 v0, v[18:21]
	s_waitcnt vmcnt(3)
	ds_write_b128 v9, v[22:25] offset:55296
	s_waitcnt vmcnt(0)
	ds_write_b128 v30, v[26:29] offset:55296
	v_add_u32_e32 v0, v163, v173
	ds_write_b128 v0, v[52:55]
	v_add_u32_e32 v0, v168, v173
	ds_write_b128 v0, v[48:51]
	v_lshl_add_u32 v0, v149, 7, v174
	v_mov_b32_e32 v1, v8
	v_lshlrev_b64 v[0:1], v147, v[0:1]
	v_lshl_add_u64 v[4:5], v[0:1], 0, v[154:155]
	v_mov_b64_e32 v[0:1], s[96:97]
	v_mad_u64_u32 v[0:1], s[14:15], v4, s20, v[0:1]
	v_mov_b32_e32 v2, v1
	v_mad_u64_u32 v[2:3], s[14:15], v5, s20, v[2:3]
	v_mov_b32_e32 v1, v2
	v_lshl_add_u64 v[0:1], v[152:153], 1, v[0:1]
	v_mov_b32_e32 v147, v8
	v_lshl_add_u64 v[0:1], v[0:1], 0, v[146:147]
	s_mov_b64 s[14:15], 0x1200
	v_lshl_add_u64 v[6:7], v[0:1], 0, s[14:15]
	s_movk_i32 s14, 0x1000
	v_add_co_u32_e32 v0, vcc, s14, v0
	s_waitcnt lgkmcnt(0)
	s_nop 0
	v_addc_co_u32_e32 v1, vcc, 0, v1, vcc
	s_barrier
	s_nop 0
	ds_read_b128 v[24:27], v215
	ds_read_b128 v[28:31], v215 offset:4608
	ds_read_b128 v[32:35], v215 offset:9216
	ds_read_b128 v[36:39], v215 offset:13824
	ds_read_b128 v[40:43], v215 offset:18432
	ds_read_b128 v[44:47], v215 offset:23040
	ds_read_b128 v[48:51], v215 offset:27648
	ds_read_b128 v[52:55], v215 offset:32256
	ds_read_b128 v[56:59], v215 offset:36864
	ds_read_b128 v[60:63], v215 offset:64
	ds_read_b128 v[64:67], v215 offset:4672
	ds_read_b128 v[68:71], v215 offset:9280
	ds_read_b128 v[72:75], v215 offset:13888
	ds_read_b128 v[76:79], v215 offset:18496
	ds_read_b128 v[80:83], v215 offset:23104
	ds_read_b128 v[84:87], v215 offset:27712
	ds_read_b128 v[88:91], v215 offset:32320
	ds_read_b128 v[92:95], v215 offset:36928
	v_mov_b32_e32 v149, v8
	v_lshlrev_b64 v[6:7], 14, v[148:149]
	v_lshl_add_u64 v[4:5], v[4:5], 0, v[6:7]
	v_lshlrev_b64 v[6:7], 9, v[4:5]
	v_lshl_add_u64 v[6:7], s[0:1], 0, v[6:7]
	v_lshl_add_u64 v[22:23], v[6:7], 0, v[150:151]
	s_waitcnt vmcnt(3) lgkmcnt(14)
	v_mfma_f32_16x16x32_bf16 v[24:27], v[24:27], v[244:247], 0
	v_mfma_f32_16x16x32_bf16 v[28:31], v[28:31], v[244:247], 0
	v_mfma_f32_16x16x32_bf16 v[32:35], v[32:35], v[244:247], 0
	v_mfma_f32_16x16x32_bf16 v[36:39], v[36:39], v[244:247], 0
	s_waitcnt lgkmcnt(13)
	v_mfma_f32_16x16x32_bf16 v[40:43], v[40:43], v[244:247], 0
	s_waitcnt lgkmcnt(12)
	v_mfma_f32_16x16x32_bf16 v[44:47], v[44:47], v[244:247], 0
	s_waitcnt lgkmcnt(11)
	v_mfma_f32_16x16x32_bf16 v[48:51], v[48:51], v[244:247], 0
	s_waitcnt lgkmcnt(10)
	v_mfma_f32_16x16x32_bf16 v[52:55], v[52:55], v[244:247], 0
	s_waitcnt lgkmcnt(9)
	v_mfma_f32_16x16x32_bf16 v[0:3], v[56:59], v[244:247], 0
	ds_read_b128 v[56:59], v215 offset:4736
	ds_read_b128 v[96:99], v215 offset:9344
	ds_read_b128 v[100:103], v215 offset:13952
	ds_read_b128 v[104:107], v215 offset:18560
	ds_read_b128 v[148:151], v215 offset:23168
	ds_read_b128 v[152:155], v215 offset:27776
	ds_read_b128 v[164:167], v215 offset:32384
	ds_read_b128 v[224:227], v215 offset:128
	ds_read_b128 v[228:231], v215 offset:36992
	s_waitcnt vmcnt(2) lgkmcnt(14)
; #define LAS __attribute__((address_space(3)))
; template <int DH, bool IS_A> ...
;     ...
; #pragma unroll
;     for (int T = 0; T < 9; ++T) { s[T] = (f32x4){0.f, 0.f, 0.f, 0.f}; kf[0][T] = *(const LAS bf16x8*)(kp + T * 16 * KS); }
; #pragma unroll
;     for (int ks = 0; ks < NKS; ++ks) {
;         if (ks + 1 < NKS) {
; #pragma unroll
;             for (int T = 0; T < 9; ++T) kf[(ks + 1) & 1][T] = *(const LAS bf16x8*)(kp + T * 16 * KS + (ks + 1) * 64); }
;         __builtin_amdgcn_sched_barrier(0);
; #pragma unroll
;         for (int T = 0; T < 9; ++T) s[T] = __builtin_amdgcn_mfma_f32_16x16x32_bf16(kf[ks & 1][T], qf[ks], s[T], 0, 0, 0);
;         __builtin_amdgcn_sched_barrier(0);
;     }
;     const int i = i0 + c16; const int jmin = max(i + (IS_A ? 1 : 0), jlo), jmax = i + 128;
;     float mx = -INFINITY;
; #pragma unroll
;     for (int T = 0; T < 9; ++T)
; #pragma unroll
;         for (int r = 0; r < 4; ++r) { const int j = i0 + 16 * T + 4 * g + r; const bool ok = (j >= jmin) && (j <= jmax); const float v = ok ? s[T][r] : -INFINITY; s[T][r] = v; mx = fmaxf(mx, v); }
;     mx = fmaxf(mx, __shfl_xor(mx, 16)); mx = fmaxf(mx, __shfl_xor(mx, 32));
;     if (IS_A) mx = fmaxf(mx, sink2);
	v_mfma_f32_16x16x32_bf16 v[24:27], v[60:63], v[248:251], v[24:27]
	v_mfma_f32_16x16x32_bf16 v[28:31], v[64:67], v[248:251], v[28:31]
	v_mfma_f32_16x16x32_bf16 v[32:35], v[68:71], v[248:251], v[32:35]
	v_mfma_f32_16x16x32_bf16 v[36:39], v[72:75], v[248:251], v[36:39]
	s_waitcnt lgkmcnt(13)
	v_mfma_f32_16x16x32_bf16 v[40:43], v[76:79], v[248:251], v[40:43]
	s_waitcnt lgkmcnt(12)
	v_mfma_f32_16x16x32_bf16 v[44:47], v[80:83], v[248:251], v[44:47]
	s_waitcnt lgkmcnt(11)
	v_mfma_f32_16x16x32_bf16 v[48:51], v[84:87], v[248:251], v[48:51]
	s_waitcnt lgkmcnt(10)
	v_mfma_f32_16x16x32_bf16 v[52:55], v[88:91], v[248:251], v[52:55]
	s_waitcnt lgkmcnt(9)
	v_mfma_f32_16x16x32_bf16 v[0:3], v[92:95], v[248:251], v[0:3]
	ds_read_b128 v[10:13], v215 offset:4800
	ds_read_b128 v[60:63], v215 offset:9408
	ds_read_b128 v[64:67], v215 offset:14016
	ds_read_b128 v[68:71], v215 offset:18624
	ds_read_b128 v[72:75], v215 offset:23232
	ds_read_b128 v[76:79], v215 offset:27840
	ds_read_b128 v[80:83], v215 offset:32448
	ds_read_b128 v[84:87], v215 offset:192
	ds_read_b128 v[88:91], v215 offset:37056
	s_waitcnt vmcnt(1) lgkmcnt(10)
	v_mfma_f32_16x16x32_bf16 v[24:27], v[224:227], v[252:255], v[24:27]
	v_mfma_f32_16x16x32_bf16 v[28:31], v[56:59], v[252:255], v[28:31]
	v_mfma_f32_16x16x32_bf16 v[32:35], v[96:99], v[252:255], v[32:35]
	v_mfma_f32_16x16x32_bf16 v[36:39], v[100:103], v[252:255], v[36:39]
	v_mfma_f32_16x16x32_bf16 v[40:43], v[104:107], v[252:255], v[40:43]
	v_mfma_f32_16x16x32_bf16 v[44:47], v[148:151], v[252:255], v[44:47]
	v_mfma_f32_16x16x32_bf16 v[48:51], v[152:155], v[252:255], v[48:51]
	v_mfma_f32_16x16x32_bf16 v[52:55], v[164:167], v[252:255], v[52:55]
	s_waitcnt lgkmcnt(9)
	v_mfma_f32_16x16x32_bf16 v[0:3], v[228:231], v[252:255], v[0:3]
	s_waitcnt vmcnt(0) lgkmcnt(1)
	v_mfma_f32_16x16x32_bf16 v[14:17], v[84:87], v[236:239], v[24:27]
	v_mfma_f32_16x16x32_bf16 v[24:27], v[60:63], v[236:239], v[32:35]
	v_mfma_f32_16x16x32_bf16 v[10:13], v[10:13], v[236:239], v[28:31]
	v_mfma_f32_16x16x32_bf16 v[28:31], v[64:67], v[236:239], v[36:39]
	v_mfma_f32_16x16x32_bf16 v[32:35], v[68:71], v[236:239], v[40:43]
	v_mfma_f32_16x16x32_bf16 v[36:39], v[72:75], v[236:239], v[44:47]
	v_mfma_f32_16x16x32_bf16 v[40:43], v[76:79], v[236:239], v[48:51]
	v_mfma_f32_16x16x32_bf16 v[44:47], v[80:83], v[236:239], v[52:55]
	s_waitcnt lgkmcnt(0)
	v_mfma_f32_16x16x32_bf16 v[0:3], v[88:91], v[236:239], v[0:3]
	v_max_i32_e32 v6, v174, v223
	v_readlane_b32 s14, v242, 14
	v_cmp_ge_u32_e32 vcc, v175, v6
	v_readlane_b32 s15, v242, 15
	s_and_b64 vcc, vcc, s[14:15]
	v_readlane_b32 s14, v242, 16
	v_cndmask_b32_e32 v7, v220, v14, vcc
	v_cmp_ge_u32_e32 vcc, v176, v6
	v_readlane_b32 s15, v242, 17
	s_and_b64 vcc, vcc, s[14:15]
	v_readlane_b32 s14, v242, 18
	v_cndmask_b32_e32 v9, v220, v15, vcc
	v_cmp_ge_u32_e32 vcc, v177, v6
	v_readlane_b32 s15, v242, 19
	s_and_b64 vcc, vcc, s[14:15]
	v_readlane_b32 s14, v242, 20
	v_cndmask_b32_e32 v15, v220, v16, vcc
	v_cmp_ge_u32_e32 vcc, v178, v6
	v_readlane_b32 s15, v242, 21
	s_and_b64 vcc, vcc, s[14:15]
	v_readlane_b32 s14, v242, 22
	v_cndmask_b32_e32 v16, v220, v17, vcc
	v_cmp_ge_u32_e32 vcc, v179, v6
	v_readlane_b32 s15, v242, 23
	s_and_b64 vcc, vcc, s[14:15]
	v_readlane_b32 s14, v242, 24
	v_cndmask_b32_e32 v10, v220, v10, vcc
	v_cmp_ge_u32_e32 vcc, v180, v6
	v_readlane_b32 s15, v242, 25
	s_and_b64 vcc, vcc, s[14:15]
	v_readlane_b32 s14, v242, 26
	v_cndmask_b32_e32 v11, v220, v11, vcc
	v_cmp_ge_u32_e32 vcc, v181, v6
	v_readlane_b32 s15, v242, 27
	s_and_b64 vcc, vcc, s[14:15]
	v_readlane_b32 s14, v242, 28
	v_cndmask_b32_e32 v12, v220, v12, vcc
	v_cmp_ge_u32_e32 vcc, v182, v6
	v_readlane_b32 s15, v242, 29
	s_and_b64 vcc, vcc, s[14:15]
	v_readlane_b32 s14, v242, 30
	v_cndmask_b32_e32 v13, v220, v13, vcc
	v_cmp_ge_u32_e32 vcc, v183, v6
	v_readlane_b32 s15, v242, 31
	s_and_b64 vcc, vcc, s[14:15]
	v_readlane_b32 s14, v242, 32
	v_cndmask_b32_e32 v17, v220, v24, vcc
	v_cmp_ge_u32_e32 vcc, v184, v6
	v_readlane_b32 s15, v242, 33
	s_and_b64 vcc, vcc, s[14:15]
	v_cndmask_b32_e32 v18, v220, v25, vcc
	v_cmp_ge_u32_e32 vcc, v185, v6
	s_and_b64 vcc, vcc, s[28:29]
	v_max3_f32 v14, v7, s21, v9
	v_cndmask_b32_e32 v19, v220, v26, vcc
	v_cmp_ge_u32_e32 vcc, v187, v6
	s_and_b64 vcc, vcc, s[30:31]
	v_max3_f32 v14, v14, v15, v16
	v_cndmask_b32_e32 v20, v220, v27, vcc
	v_cmp_ge_u32_e32 vcc, v188, v6
	s_and_b64 vcc, vcc, s[34:35]
	v_max3_f32 v14, v14, v10, v11
	v_cndmask_b32_e32 v21, v220, v28, vcc
	v_cmp_ge_u32_e32 vcc, v189, v6
	s_and_b64 vcc, vcc, s[36:37]
	v_max3_f32 v14, v14, v12, v13
	v_cndmask_b32_e32 v24, v220, v29, vcc
	v_cmp_ge_u32_e32 vcc, v190, v6
	s_and_b64 vcc, vcc, s[38:39]
	v_max3_f32 v14, v14, v17, v18
	v_cndmask_b32_e32 v26, v220, v30, vcc
	v_cmp_ge_u32_e32 vcc, v191, v6
	s_and_b64 vcc, vcc, s[40:41]
	v_max3_f32 v14, v14, v19, v20
	v_cndmask_b32_e32 v27, v220, v31, vcc
	v_cmp_ge_u32_e32 vcc, v193, v6
	s_and_b64 vcc, vcc, s[42:43]
	v_max3_f32 v14, v14, v21, v24
	v_cndmask_b32_e32 v28, v220, v32, vcc
	v_cmp_ge_u32_e32 vcc, v194, v6
	s_and_b64 vcc, vcc, s[44:45]
	v_max3_f32 v14, v14, v26, v27
	v_cndmask_b32_e32 v29, v220, v33, vcc
	v_cmp_ge_u32_e32 vcc, v195, v6
	s_and_b64 vcc, vcc, s[46:47]
	v_max3_f32 v14, v14, v28, v29
	v_cndmask_b32_e32 v30, v220, v34, vcc
	v_cmp_ge_u32_e32 vcc, v196, v6
	s_and_b64 vcc, vcc, s[48:49]
	v_cndmask_b32_e64 v0, v220, v0, s[76:77]
	v_cndmask_b32_e32 v31, v220, v35, vcc
	v_cmp_ge_u32_e32 vcc, v197, v6
	s_and_b64 vcc, vcc, s[50:51]
	v_max3_f32 v14, v14, v30, v31
	v_cndmask_b32_e32 v32, v220, v36, vcc
	v_cmp_ge_u32_e32 vcc, v198, v6
	s_and_b64 vcc, vcc, s[52:53]
	v_and_b32_e32 v25, 64, v221
	v_cndmask_b32_e32 v33, v220, v37, vcc
; #define LAS __attribute__((address_space(3)))
; __device__ __forceinline__ unsigned cvt_pk_bf16(float lo, float hi) { unsigned r; asm volatile("v_cvt_pk_bf16_f32 %0, %1, %2" : "=v"(r) : "v"(lo), "v"(hi)); return r; }
; __device__ __forceinline__ float fast_rcp(float x) { return __builtin_amdgcn_rcpf(x); }
; __device__ __forceinline__ float fast_exp2(float x) { return __builtin_amdgcn_exp2f(x); }
; template <int DH, bool IS_A> ...
;     ...
;         for (int r = 0; r < 4; ++r) { const int j = i0 + 16 * T + 4 * g + r; const bool ok = (j >= jmin) && (j <= jmax); const float v = ok ? s[T][r] : -INFINITY; s[T][r] = v; mx = fmaxf(mx, v); }
;     mx = fmaxf(mx, __shfl_xor(mx, 16)); mx = fmaxf(mx, __shfl_xor(mx, 32));
;     if (IS_A) mx = fmaxf(mx, sink2);
;     float sum = 0.f;
; #pragma unroll
;     for (int T = 0; T < 9; ++T)
; #pragma unroll
;         for (int r = 0; r < 4; ++r) { const float p = fast_exp2(s[T][r] - mx); s[T][r] = p; sum += p; }
;     sum += __shfl_xor(sum, 16); sum += __shfl_xor(sum, 32);
;     if (IS_A) sum += fast_exp2(sink2 - mx);
;     bf16x8 pf[4];
; #pragma unroll
;     for (int k = 0; k < 4; ++k) { u32x4 w; w.x = cvt_pk_bf16(s[2 * k][0], s[2 * k][1]); w.y = cvt_pk_bf16(s[2 * k][2], s[2 * k][3]); w.z = cvt_pk_bf16(s[2 * k + 1][0], s[2 * k + 1][1]); w.w = cvt_pk_bf16(s[2 * k + 1][2], s[2 * k + 1][3]);
;         pf[k] = __builtin_bit_cast(bf16x8, w); }
;     bf16x4 p8; { u32x2 w; w.x = cvt_pk_bf16(s[8][0], s[8][1]); w.y = cvt_pk_bf16(s[8][2], s[8][3]); p8 = __builtin_bit_cast(bf16x4, w); }
;     const int q4 = c16 >> 2, p4 = c16 & 3;
;     const LAS unsigned char* vp = Vl + (i0 + 4 * g + q4) * VS + 8 * p4;
;     const float inv = fast_rcp(sum);
;     bf16x4 vv[2][9];
; #pragma unroll
;     for (int r9 = 0; r9 < 9; ++r9) vv[0][r9] = __builtin_amdgcn_ds_read_tr16_b64_v4i16((LAS bf16x4*)(vp + (16 * r9) * VS));
	v_cmp_ge_u32_e32 vcc, v199, v6
	s_and_b64 vcc, vcc, s[54:55]
	v_max3_f32 v14, v14, v32, v33
	v_cndmask_b32_e32 v34, v220, v38, vcc
	v_cmp_ge_u32_e32 vcc, v200, v6
	s_and_b64 vcc, vcc, s[56:57]
	v_add_u32_e32 v25, 64, v25
	v_cndmask_b32_e32 v35, v220, v39, vcc
	v_cmp_ge_u32_e32 vcc, v201, v6
	s_and_b64 vcc, vcc, s[58:59]
	v_max3_f32 v14, v14, v34, v35
	v_cndmask_b32_e32 v36, v220, v40, vcc
	v_cmp_ge_u32_e32 vcc, v202, v6
	s_and_b64 vcc, vcc, s[26:27]
	v_lshl_add_u64 v[22:23], v[22:23], 0, v[128:129]
	v_cndmask_b32_e32 v37, v220, v41, vcc
	v_cmp_ge_u32_e32 vcc, v203, v6
	s_and_b64 vcc, vcc, s[62:63]
	v_max3_f32 v14, v14, v36, v37
	v_cndmask_b32_e32 v38, v220, v42, vcc
	v_cmp_ge_u32_e32 vcc, v204, v6
	s_and_b64 vcc, vcc, s[64:65]
	s_nop 0
	v_cndmask_b32_e32 v39, v220, v43, vcc
	v_cmp_ge_u32_e32 vcc, v205, v6
	s_and_b64 vcc, vcc, s[66:67]
	v_max3_f32 v14, v14, v38, v39
	v_cndmask_b32_e32 v40, v220, v44, vcc
	v_cmp_ge_u32_e32 vcc, v206, v6
	s_and_b64 vcc, vcc, s[68:69]
	s_nop 0
	v_cndmask_b32_e32 v41, v220, v45, vcc
	v_cmp_ge_u32_e32 vcc, v207, v6
	s_and_b64 vcc, vcc, s[24:25]
	v_max3_f32 v14, v14, v40, v41
	v_cndmask_b32_e32 v42, v220, v46, vcc
	v_cmp_ge_u32_e32 vcc, v208, v6
	s_and_b64 vcc, vcc, s[72:73]
	s_nop 0
	v_cndmask_b32_e32 v43, v220, v47, vcc
	v_cmp_ge_u32_e32 vcc, v209, v6
	s_and_b64 vcc, vcc, s[78:79]
	v_max3_f32 v14, v14, v42, v43
	v_cndmask_b32_e32 v1, v220, v1, vcc
	v_cmp_ge_u32_e32 vcc, v210, v6
	s_and_b64 vcc, vcc, s[80:81]
	v_max3_f32 v14, v14, v0, v1
	v_cndmask_b32_e32 v2, v220, v2, vcc
	v_cmp_ge_u32_e32 vcc, v211, v6
	s_and_b64 vcc, vcc, s[82:83]
	s_nop 0
	v_cndmask_b32_e32 v3, v220, v3, vcc
	v_max3_f32 v6, v14, v2, v3
	v_xor_b32_e32 v14, 16, v221
	v_cmp_lt_i32_e32 vcc, v14, v25
	s_nop 1
	v_cndmask_b32_e32 v14, v221, v14, vcc
	v_lshlrev_b32_e32 v14, 2, v14
	ds_bpermute_b32 v44, v14, v6
	s_waitcnt lgkmcnt(0)
	v_max_f32_e32 v44, v44, v44
	v_max_f32_e32 v6, v6, v44
	v_xor_b32_e32 v44, 32, v221
	v_cmp_lt_i32_e32 vcc, v44, v25
	s_nop 1
	v_cndmask_b32_e32 v25, v221, v44, vcc
	v_lshlrev_b32_e32 v44, 2, v25
	ds_bpermute_b32 v25, v44, v6
	s_waitcnt lgkmcnt(0)
	v_max_f32_e32 v25, v25, v25
	v_max_f32_e32 v25, v6, v25
	v_sub_f32_e32 v6, v7, v25
	v_exp_f32_e32 v6, v6
	v_sub_f32_e32 v9, v9, v25
	v_exp_f32_e32 v9, v9
	v_sub_f32_e32 v15, v15, v25
	v_exp_f32_e32 v15, v15
	v_sub_f32_e32 v16, v16, v25
	v_exp_f32_e32 v16, v16
	v_sub_f32_e32 v10, v10, v25
	v_add_f32_e32 v7, 0, v6
	v_exp_f32_e32 v10, v10
	v_sub_f32_e32 v11, v11, v25
	v_add_f32_e32 v7, v9, v7
	v_exp_f32_e32 v11, v11
	v_sub_f32_e32 v12, v12, v25
	v_add_f32_e32 v7, v15, v7
	v_exp_f32_e32 v12, v12
	v_sub_f32_e32 v13, v13, v25
	v_add_f32_e32 v7, v16, v7
	v_exp_f32_e32 v13, v13
	v_sub_f32_e32 v17, v17, v25
	v_add_f32_e32 v7, v10, v7
	v_exp_f32_e32 v17, v17
	v_sub_f32_e32 v18, v18, v25
	v_add_f32_e32 v7, v11, v7
	v_exp_f32_e32 v18, v18
	v_sub_f32_e32 v19, v19, v25
	v_add_f32_e32 v7, v12, v7
	v_exp_f32_e32 v19, v19
	v_sub_f32_e32 v20, v20, v25
	v_add_f32_e32 v7, v13, v7
	v_exp_f32_e32 v20, v20
	v_sub_f32_e32 v21, v21, v25
	v_add_f32_e32 v7, v17, v7
	v_exp_f32_e32 v21, v21
	v_sub_f32_e32 v24, v24, v25
	v_add_f32_e32 v7, v18, v7
	v_exp_f32_e32 v24, v24
	v_sub_f32_e32 v26, v26, v25
	v_add_f32_e32 v7, v19, v7
	v_exp_f32_e32 v26, v26
	v_sub_f32_e32 v27, v27, v25
	v_add_f32_e32 v7, v20, v7
	v_exp_f32_e32 v27, v27
	v_sub_f32_e32 v28, v28, v25
	v_add_f32_e32 v7, v21, v7
	v_exp_f32_e32 v28, v28
	v_sub_f32_e32 v29, v29, v25
	v_add_f32_e32 v7, v24, v7
	v_exp_f32_e32 v29, v29
	v_sub_f32_e32 v30, v30, v25
	v_add_f32_e32 v7, v26, v7
	v_exp_f32_e32 v30, v30
	v_sub_f32_e32 v31, v31, v25
	v_add_f32_e32 v7, v27, v7
	v_exp_f32_e32 v31, v31
	v_sub_f32_e32 v32, v32, v25
	v_add_f32_e32 v7, v28, v7
	v_exp_f32_e32 v32, v32
	v_sub_f32_e32 v33, v33, v25
	v_add_f32_e32 v7, v29, v7
	v_exp_f32_e32 v33, v33
	v_sub_f32_e32 v34, v34, v25
	v_add_f32_e32 v7, v30, v7
	v_exp_f32_e32 v34, v34
	v_sub_f32_e32 v35, v35, v25
	v_add_f32_e32 v7, v31, v7
	v_exp_f32_e32 v35, v35
	v_sub_f32_e32 v36, v36, v25
	v_add_f32_e32 v7, v32, v7
	v_exp_f32_e32 v36, v36
	v_sub_f32_e32 v37, v37, v25
	v_add_f32_e32 v7, v33, v7
	v_exp_f32_e32 v37, v37
	v_sub_f32_e32 v38, v38, v25
	v_add_f32_e32 v7, v34, v7
	v_exp_f32_e32 v38, v38
	v_sub_f32_e32 v39, v39, v25
	v_add_f32_e32 v7, v35, v7
	v_exp_f32_e32 v39, v39
	v_sub_f32_e32 v40, v40, v25
	v_add_f32_e32 v7, v36, v7
	v_exp_f32_e32 v40, v40
	v_sub_f32_e32 v41, v41, v25
	v_add_f32_e32 v7, v37, v7
	v_exp_f32_e32 v41, v41
	v_sub_f32_e32 v42, v42, v25
	v_add_f32_e32 v7, v38, v7
	v_exp_f32_e32 v42, v42
	v_sub_f32_e32 v43, v43, v25
	v_add_f32_e32 v7, v39, v7
	v_exp_f32_e32 v43, v43
	v_sub_f32_e32 v0, v0, v25
	v_add_f32_e32 v7, v40, v7
	v_exp_f32_e32 v45, v0
	v_add_f32_e32 v7, v41, v7
	v_add_f32_e32 v7, v42, v7
	v_add_f32_e32 v7, v43, v7
	v_sub_f32_e32 v1, v1, v25
	v_add_f32_e32 v0, v45, v7
	v_exp_f32_e32 v7, v1
	v_sub_f32_e32 v1, v2, v25
	v_exp_f32_e32 v46, v1
	v_sub_f32_e32 v1, v3, v25
	v_exp_f32_e32 v47, v1
	v_add_f32_e32 v0, v7, v0
	v_add_f32_e32 v0, v46, v0
	v_add_f32_e32 v0, v47, v0
	ds_bpermute_b32 v1, v14, v0
	s_waitcnt lgkmcnt(0)
	v_add_f32_e32 v48, v0, v1
	ds_bpermute_b32 v49, v44, v48
	v_cvt_pk_bf16_f32 v0, v6, v9
	v_cvt_pk_bf16_f32 v1, v15, v16
	v_cvt_pk_bf16_f32 v2, v10, v11
	v_cvt_pk_bf16_f32 v3, v12, v13
	v_cvt_pk_bf16_f32 v10, v17, v18
	v_cvt_pk_bf16_f32 v11, v19, v20
	v_cvt_pk_bf16_f32 v12, v21, v24
	v_cvt_pk_bf16_f32 v13, v26, v27
	v_cvt_pk_bf16_f32 v14, v28, v29
	v_cvt_pk_bf16_f32 v15, v30, v31
	v_cvt_pk_bf16_f32 v16, v32, v33
	v_cvt_pk_bf16_f32 v17, v34, v35
	v_cvt_pk_bf16_f32 v18, v36, v37
	v_cvt_pk_bf16_f32 v19, v38, v39
	v_cvt_pk_bf16_f32 v20, v40, v41
	v_cvt_pk_bf16_f32 v21, v42, v43
	v_cvt_pk_bf16_f32 v6, v45, v7
	v_cvt_pk_bf16_f32 v7, v46, v47
	ds_read_b64_tr_b16 v[30:31], v212 offset:4608
	ds_read_b64_tr_b16 v[32:33], v212 offset:9216
	ds_read_b64_tr_b16 v[34:35], v212 offset:13824
	ds_read_b64_tr_b16 v[36:37], v212 offset:18432
	ds_read_b64_tr_b16 v[38:39], v212 offset:23040
	ds_read_b64_tr_b16 v[40:41], v212 offset:27648
	ds_read_b64_tr_b16 v[42:43], v212 offset:32256
	ds_read_b64_tr_b16 v[44:45], v212 offset:36864
	s_waitcnt lgkmcnt(8)
; #define LAS __attribute__((address_space(3)))
; template <int DH, bool IS_A> ...
;     ...
;     for (int r9 = 0; r9 < 9; ++r9) vv[0][r9] = __builtin_amdgcn_ds_read_tr16_b64_v4i16((LAS bf16x4*)(vp + (16 * r9) * VS));
; #pragma unroll
;     for (int dt = 0; dt < NDT; ++dt) {
;         if (dt + 1 < NDT) {
; #pragma unroll
;             for (int r9 = 0; r9 < 9; ++r9) vv[(dt + 1) & 1][r9] = __builtin_amdgcn_ds_read_tr16_b64_v4i16((LAS bf16x4*)(vp + (16 * r9) * VS + (dt + 1) * 32)); }
;         __builtin_amdgcn_sched_barrier(0);
;         f32x4 o = (f32x4){0.f, 0.f, 0.f, 0.f};
; #pragma unroll
;         for (int k = 0; k < 4; ++k) {
;             const bf16x4 lo = vv[dt & 1][2 * k], hi = vv[dt & 1][2 * k + 1];
;             o = __builtin_amdgcn_mfma_f32_16x16x32_bf16((bf16x8){lo[0], lo[1], lo[2], lo[3], hi[0], hi[1], hi[2], hi[3]}, pf[k], o, 0, 0, 0);
;         }
;         { const bf16x4 l8 = vv[dt & 1][8];
;           o = __builtin_amdgcn_mfma_f32_16x16x32_bf16((bf16x8){l8[0], l8[1], l8[2], l8[3], l8[0], l8[1], l8[2], l8[3]}, (bf16x8){p8[0], p8[1], p8[2], p8[3], 0, 0, 0, 0}, o, 0, 0, 0); }
;         __builtin_amdgcn_sched_barrier(0);
;         o = o * inv;
;         if (IS_A) { typedef float f2 __attribute__((ext_vector_type(2))); const f2 ga = __builtin_amdgcn_cvt_pk_f32_fp8((int)gwv[dt].x, false), gb = __builtin_amdgcn_cvt_pk_f32_fp8((int)gwv[dt].x, true);
;             o[0] *= ga[0] * SU8; o[1] *= ga[1] * SU8; o[2] *= gb[0] * SU8; o[3] *= gb[1] * SU8;
;             *(unsigned*)(u8row + 16 * dt + 4 * g) = pack_fp8x4(o[0], o[1], o[2], o[3]); }
;         else *(unsigned*)((unsigned char*)orow + 16 * dt + 4 * g) = pack_fp8x4(o[0] * SU8, o[1] * SU8, o[2] * SU8, o[3] * SU8);
	v_add_f32_e32 v26, v48, v49
	ds_read_b64_tr_b16 v[28:29], v212
	ds_read_b64_tr_b16 v[48:49], v212 offset:32
	ds_read_b64_tr_b16 v[50:51], v212 offset:4640
	ds_read_b64_tr_b16 v[52:53], v212 offset:9248
	ds_read_b64_tr_b16 v[54:55], v212 offset:13856
	ds_read_b64_tr_b16 v[56:57], v212 offset:18464
	ds_read_b64_tr_b16 v[58:59], v212 offset:23072
	ds_read_b64_tr_b16 v[60:61], v212 offset:27680
	ds_read_b64_tr_b16 v[62:63], v212 offset:32288
	ds_read_b64_tr_b16 v[64:65], v212 offset:36896
	v_rcp_f32_e32 v24, v26
	v_mov_b32_e32 v9, v8
	s_waitcnt lgkmcnt(9)
	v_mfma_f32_16x16x32_bf16 v[28:31], v[28:31], v[0:3], 0
	v_mov_b32_e32 v46, v44
	v_mov_b32_e32 v47, v45
	v_mfma_f32_16x16x32_bf16 v[28:31], v[32:35], v[10:13], v[28:31]
	v_mfma_f32_16x16x32_bf16 v[28:31], v[36:39], v[14:17], v[28:31]
	v_mfma_f32_16x16x32_bf16 v[28:31], v[40:43], v[18:21], v[28:31]
	v_mfma_f32_16x16x32_bf16 v[28:31], v[44:47], v[6:9], v[28:31]
	s_nop 7
	v_pk_mul_f32 v[30:31], v[30:31], v[24:25] op_sel_hi:[1,0]
	v_pk_mul_f32 v[28:29], v[28:29], v[24:25] op_sel_hi:[1,0]
	s_nop 0
	v_mul_f32_e32 v27, 0x41800000, v28
	v_mul_f32_e32 v28, 0x41800000, v29
	v_mul_f32_e32 v29, 0x41800000, v30
	v_mul_f32_e32 v30, 0x41800000, v31
	v_mov_b32_e32 v31, v8
	v_cvt_pk_fp8_f32 v31, v27, v28
	v_mov_b32_e32 v27, v8
	v_cvt_pk_fp8_f32 v27, v29, v30
	v_and_b32_e32 v28, 0xffff, v31
	v_lshl_or_b32 v27, v27, 16, v28
	global_store_dword v[22:23], v27, off
	ds_read_b64_tr_b16 v[28:29], v212 offset:64
	ds_read_b64_tr_b16 v[30:31], v212 offset:4672
	ds_read_b64_tr_b16 v[32:33], v212 offset:9280
	ds_read_b64_tr_b16 v[34:35], v212 offset:13888
	ds_read_b64_tr_b16 v[36:37], v212 offset:18496
	ds_read_b64_tr_b16 v[38:39], v212 offset:23104
	ds_read_b64_tr_b16 v[40:41], v212 offset:27712
	ds_read_b64_tr_b16 v[42:43], v212 offset:32320
	ds_read_b64_tr_b16 v[44:45], v212 offset:36928
	s_waitcnt lgkmcnt(14)
	v_mfma_f32_16x16x32_bf16 v[46:49], v[48:51], v[0:3], 0
	s_waitcnt lgkmcnt(9)
	v_mov_b32_e32 v66, v64
	v_mov_b32_e32 v67, v65
	v_mfma_f32_16x16x32_bf16 v[46:49], v[52:55], v[10:13], v[46:49]
	v_mfma_f32_16x16x32_bf16 v[46:49], v[56:59], v[14:17], v[46:49]
	v_mfma_f32_16x16x32_bf16 v[46:49], v[60:63], v[18:21], v[46:49]
	v_mfma_f32_16x16x32_bf16 v[46:49], v[64:67], v[6:9], v[46:49]
	s_nop 7
	v_pk_mul_f32 v[48:49], v[48:49], v[24:25] op_sel_hi:[1,0]
	v_pk_mul_f32 v[46:47], v[46:47], v[24:25] op_sel_hi:[1,0]
	s_nop 0
	v_mul_f32_e32 v27, 0x41800000, v46
	v_mul_f32_e32 v46, 0x41800000, v47
	v_mul_f32_e32 v47, 0x41800000, v48
	v_mul_f32_e32 v48, 0x41800000, v49
	v_mov_b32_e32 v49, v8
	v_cvt_pk_fp8_f32 v49, v27, v46
	v_mov_b32_e32 v27, v8
	v_cvt_pk_fp8_f32 v27, v47, v48
	v_and_b32_e32 v46, 0xffff, v49
	v_lshl_or_b32 v27, v27, 16, v46
	global_store_dword v[22:23], v27, off offset:16
	ds_read_b64_tr_b16 v[48:49], v212 offset:96
	ds_read_b64_tr_b16 v[50:51], v212 offset:4704
	ds_read_b64_tr_b16 v[52:53], v212 offset:9312
	ds_read_b64_tr_b16 v[54:55], v212 offset:13920
	ds_read_b64_tr_b16 v[56:57], v212 offset:18528
	ds_read_b64_tr_b16 v[58:59], v212 offset:23136
	ds_read_b64_tr_b16 v[60:61], v212 offset:27744
	ds_read_b64_tr_b16 v[62:63], v212 offset:32352
	ds_read_b64_tr_b16 v[64:65], v212 offset:36960
	s_waitcnt lgkmcnt(14)
	v_mfma_f32_16x16x32_bf16 v[28:31], v[28:31], v[0:3], 0
	s_waitcnt lgkmcnt(9)
	v_mov_b32_e32 v46, v44
	v_mov_b32_e32 v47, v45
	v_mfma_f32_16x16x32_bf16 v[28:31], v[32:35], v[10:13], v[28:31]
	v_mfma_f32_16x16x32_bf16 v[28:31], v[36:39], v[14:17], v[28:31]
	v_mfma_f32_16x16x32_bf16 v[28:31], v[40:43], v[18:21], v[28:31]
	v_mfma_f32_16x16x32_bf16 v[28:31], v[44:47], v[6:9], v[28:31]
	s_nop 7
	v_pk_mul_f32 v[30:31], v[24:25], v[30:31] op_sel_hi:[0,1]
	v_pk_mul_f32 v[28:29], v[24:25], v[28:29] op_sel_hi:[0,1]
	v_mul_f32_e32 v27, 0x41800000, v28
	v_mul_f32_e32 v28, 0x41800000, v29
	v_mul_f32_e32 v29, 0x41800000, v30
	v_mul_f32_e32 v30, 0x41800000, v31
	v_mov_b32_e32 v31, v8
	v_cvt_pk_fp8_f32 v31, v27, v28
	v_mov_b32_e32 v27, v8
	v_cvt_pk_fp8_f32 v27, v29, v30
	v_and_b32_e32 v28, 0xffff, v31
	v_lshl_or_b32 v27, v27, 16, v28
	global_store_dword v[22:23], v27, off offset:32
	ds_read_b64_tr_b16 v[28:29], v212 offset:128
	ds_read_b64_tr_b16 v[30:31], v212 offset:4736
	ds_read_b64_tr_b16 v[32:33], v212 offset:9344
	ds_read_b64_tr_b16 v[34:35], v212 offset:13952
	ds_read_b64_tr_b16 v[36:37], v212 offset:18560
	ds_read_b64_tr_b16 v[38:39], v212 offset:23168
	ds_read_b64_tr_b16 v[40:41], v212 offset:27776
	ds_read_b64_tr_b16 v[42:43], v212 offset:32384
	ds_read_b64_tr_b16 v[44:45], v212 offset:36992
	s_waitcnt lgkmcnt(14)
	v_mfma_f32_16x16x32_bf16 v[46:49], v[48:51], v[0:3], 0
	s_waitcnt lgkmcnt(9)
	v_mov_b32_e32 v66, v64
	v_mov_b32_e32 v67, v65
	v_mfma_f32_16x16x32_bf16 v[46:49], v[52:55], v[10:13], v[46:49]
	v_mfma_f32_16x16x32_bf16 v[46:49], v[56:59], v[14:17], v[46:49]
	v_mfma_f32_16x16x32_bf16 v[46:49], v[60:63], v[18:21], v[46:49]
	v_mfma_f32_16x16x32_bf16 v[46:49], v[64:67], v[6:9], v[46:49]
	s_nop 7
	v_pk_mul_f32 v[48:49], v[24:25], v[48:49] op_sel_hi:[0,1]
	v_pk_mul_f32 v[46:47], v[24:25], v[46:47] op_sel_hi:[0,1]
	v_mul_f32_e32 v27, 0x41800000, v46
	v_mul_f32_e32 v46, 0x41800000, v47
	v_mul_f32_e32 v47, 0x41800000, v48
	v_mul_f32_e32 v48, 0x41800000, v49
	v_mov_b32_e32 v49, v8
	v_cvt_pk_fp8_f32 v49, v27, v46
	v_mov_b32_e32 v27, v8
	v_cvt_pk_fp8_f32 v27, v47, v48
	v_and_b32_e32 v46, 0xffff, v49
	v_lshl_or_b32 v27, v27, 16, v46
	global_store_dword v[22:23], v27, off offset:48
	ds_read_b64_tr_b16 v[48:49], v212 offset:160
	ds_read_b64_tr_b16 v[50:51], v212 offset:4768
	ds_read_b64_tr_b16 v[52:53], v212 offset:9376
	ds_read_b64_tr_b16 v[54:55], v212 offset:13984
	ds_read_b64_tr_b16 v[56:57], v212 offset:18592
	ds_read_b64_tr_b16 v[58:59], v212 offset:23200
	ds_read_b64_tr_b16 v[60:61], v212 offset:27808
	ds_read_b64_tr_b16 v[62:63], v212 offset:32416
	ds_read_b64_tr_b16 v[64:65], v212 offset:37024
	s_waitcnt lgkmcnt(14)
; #define LAS __attribute__((address_space(3)))
; template <int DH, bool IS_A> ...
;     ...
;     for (int dt = 0; dt < NDT; ++dt) {
;         if (dt + 1 < NDT) {
; #pragma unroll
;             for (int r9 = 0; r9 < 9; ++r9) vv[(dt + 1) & 1][r9] = __builtin_amdgcn_ds_read_tr16_b64_v4i16((LAS bf16x4*)(vp + (16 * r9) * VS + (dt + 1) * 32)); }
;         __builtin_amdgcn_sched_barrier(0);
;         f32x4 o = (f32x4){0.f, 0.f, 0.f, 0.f};
; #pragma unroll
;         for (int k = 0; k < 4; ++k) {
;             const bf16x4 lo = vv[dt & 1][2 * k], hi = vv[dt & 1][2 * k + 1];
;             o = __builtin_amdgcn_mfma_f32_16x16x32_bf16((bf16x8){lo[0], lo[1], lo[2], lo[3], hi[0], hi[1], hi[2], hi[3]}, pf[k], o, 0, 0, 0);
;         }
;         { const bf16x4 l8 = vv[dt & 1][8];
;           o = __builtin_amdgcn_mfma_f32_16x16x32_bf16((bf16x8){l8[0], l8[1], l8[2], l8[3], l8[0], l8[1], l8[2], l8[3]}, (bf16x8){p8[0], p8[1], p8[2], p8[3], 0, 0, 0, 0}, o, 0, 0, 0); }
;         __builtin_amdgcn_sched_barrier(0);
;         o = o * inv;
;         if (IS_A) { typedef float f2 __attribute__((ext_vector_type(2))); const f2 ga = __builtin_amdgcn_cvt_pk_f32_fp8((int)gwv[dt].x, false), gb = __builtin_amdgcn_cvt_pk_f32_fp8((int)gwv[dt].x, true);
;             o[0] *= ga[0] * SU8; o[1] *= ga[1] * SU8; o[2] *= gb[0] * SU8; o[3] *= gb[1] * SU8;
;             *(unsigned*)(u8row + 16 * dt + 4 * g) = pack_fp8x4(o[0], o[1], o[2], o[3]); }
;         else *(unsigned*)((unsigned char*)orow + 16 * dt + 4 * g) = pack_fp8x4(o[0] * SU8, o[1] * SU8, o[2] * SU8, o[3] * SU8);
;     }
;     if (!IS_A) { if (g == 0) *lse_ptr = mx + __builtin_amdgcn_logf(sum); }
	v_mfma_f32_16x16x32_bf16 v[28:31], v[28:31], v[0:3], 0
	s_waitcnt lgkmcnt(9)
	v_mov_b32_e32 v46, v44
	v_mov_b32_e32 v47, v45
	v_mfma_f32_16x16x32_bf16 v[28:31], v[32:35], v[10:13], v[28:31]
	v_mfma_f32_16x16x32_bf16 v[28:31], v[36:39], v[14:17], v[28:31]
	v_mfma_f32_16x16x32_bf16 v[28:31], v[40:43], v[18:21], v[28:31]
	v_mfma_f32_16x16x32_bf16 v[28:31], v[44:47], v[6:9], v[28:31]
	s_nop 7
	v_pk_mul_f32 v[30:31], v[24:25], v[30:31] op_sel_hi:[0,1]
	v_pk_mul_f32 v[28:29], v[24:25], v[28:29] op_sel_hi:[0,1]
	v_mul_f32_e32 v27, 0x41800000, v28
	v_mul_f32_e32 v28, 0x41800000, v29
	v_mul_f32_e32 v29, 0x41800000, v30
	v_mul_f32_e32 v30, 0x41800000, v31
	v_mov_b32_e32 v31, v8
	v_cvt_pk_fp8_f32 v31, v27, v28
	v_mov_b32_e32 v27, v8
	v_cvt_pk_fp8_f32 v27, v29, v30
	v_and_b32_e32 v28, 0xffff, v31
	v_lshl_or_b32 v27, v27, 16, v28
	global_store_dword v[22:23], v27, off offset:64
	ds_read_b64_tr_b16 v[28:29], v212 offset:192
	ds_read_b64_tr_b16 v[30:31], v212 offset:4800
	ds_read_b64_tr_b16 v[32:33], v212 offset:9408
	ds_read_b64_tr_b16 v[34:35], v212 offset:14016
	ds_read_b64_tr_b16 v[36:37], v212 offset:18624
	ds_read_b64_tr_b16 v[38:39], v212 offset:23232
	ds_read_b64_tr_b16 v[40:41], v212 offset:27840
	ds_read_b64_tr_b16 v[42:43], v212 offset:32448
	ds_read_b64_tr_b16 v[44:45], v212 offset:37056
	s_waitcnt lgkmcnt(14)
	v_mfma_f32_16x16x32_bf16 v[46:49], v[48:51], v[0:3], 0
	s_waitcnt lgkmcnt(9)
	v_mov_b32_e32 v66, v64
	v_mov_b32_e32 v67, v65
	v_mfma_f32_16x16x32_bf16 v[46:49], v[52:55], v[10:13], v[46:49]
	v_mfma_f32_16x16x32_bf16 v[46:49], v[56:59], v[14:17], v[46:49]
	v_mfma_f32_16x16x32_bf16 v[46:49], v[60:63], v[18:21], v[46:49]
	v_mfma_f32_16x16x32_bf16 v[46:49], v[64:67], v[6:9], v[46:49]
	s_nop 7
	v_pk_mul_f32 v[48:49], v[24:25], v[48:49] op_sel_hi:[0,1]
	v_pk_mul_f32 v[46:47], v[24:25], v[46:47] op_sel_hi:[0,1]
	v_mul_f32_e32 v27, 0x41800000, v46
	v_mul_f32_e32 v46, 0x41800000, v47
	v_mul_f32_e32 v47, 0x41800000, v48
	v_mul_f32_e32 v48, 0x41800000, v49
	v_mov_b32_e32 v49, v8
	v_cvt_pk_fp8_f32 v49, v27, v46
	v_mov_b32_e32 v27, v8
	v_cvt_pk_fp8_f32 v27, v47, v48
	v_and_b32_e32 v46, 0xffff, v49
	v_lshl_or_b32 v27, v27, 16, v46
	global_store_dword v[22:23], v27, off offset:80
	ds_read_b64_tr_b16 v[48:49], v212 offset:224
	ds_read_b64_tr_b16 v[50:51], v212 offset:4832
	ds_read_b64_tr_b16 v[52:53], v212 offset:9440
	ds_read_b64_tr_b16 v[54:55], v212 offset:14048
	ds_read_b64_tr_b16 v[56:57], v212 offset:18656
	ds_read_b64_tr_b16 v[58:59], v212 offset:23264
	ds_read_b64_tr_b16 v[60:61], v212 offset:27872
	ds_read_b64_tr_b16 v[62:63], v212 offset:32480
	ds_read_b64_tr_b16 v[64:65], v212 offset:37088
	s_waitcnt lgkmcnt(14)
	v_mfma_f32_16x16x32_bf16 v[28:31], v[28:31], v[0:3], 0
	s_waitcnt lgkmcnt(9)
	v_mov_b32_e32 v46, v44
	v_mov_b32_e32 v47, v45
	v_mfma_f32_16x16x32_bf16 v[28:31], v[32:35], v[10:13], v[28:31]
	v_mfma_f32_16x16x32_bf16 v[28:31], v[36:39], v[14:17], v[28:31]
	v_mfma_f32_16x16x32_bf16 v[28:31], v[40:43], v[18:21], v[28:31]
	v_mfma_f32_16x16x32_bf16 v[28:31], v[44:47], v[6:9], v[28:31]
	s_nop 7
	v_pk_mul_f32 v[30:31], v[24:25], v[30:31] op_sel_hi:[0,1]
	v_pk_mul_f32 v[28:29], v[24:25], v[28:29] op_sel_hi:[0,1]
	v_mul_f32_e32 v27, 0x41800000, v28
	v_mul_f32_e32 v28, 0x41800000, v29
	v_mul_f32_e32 v29, 0x41800000, v30
	v_mul_f32_e32 v30, 0x41800000, v31
	v_mov_b32_e32 v31, v8
	v_cvt_pk_fp8_f32 v31, v27, v28
	v_mov_b32_e32 v27, v8
	v_cvt_pk_fp8_f32 v27, v29, v30
	v_and_b32_e32 v28, 0xffff, v31
	v_lshl_or_b32 v27, v27, 16, v28
	global_store_dword v[22:23], v27, off offset:96
	s_waitcnt lgkmcnt(7)
	v_mfma_f32_16x16x32_bf16 v[0:3], v[48:51], v[0:3], 0
	s_waitcnt lgkmcnt(0)
	v_mov_b32_e32 v66, v64
	v_mov_b32_e32 v67, v65
	v_mfma_f32_16x16x32_bf16 v[0:3], v[52:55], v[10:13], v[0:3]
	v_mfma_f32_16x16x32_bf16 v[0:3], v[56:59], v[14:17], v[0:3]
	v_mfma_f32_16x16x32_bf16 v[0:3], v[60:63], v[18:21], v[0:3]
	v_mfma_f32_16x16x32_bf16 v[0:3], v[64:67], v[6:9], v[0:3]
	s_nop 7
	v_pk_mul_f32 v[0:1], v[24:25], v[0:1] op_sel_hi:[0,1]
	v_pk_mul_f32 v[2:3], v[24:25], v[2:3] op_sel_hi:[0,1]
	v_mul_f32_e32 v0, 0x41800000, v0
	v_mul_f32_e32 v1, 0x41800000, v1
	v_mov_b32_e32 v6, v8
	v_mul_f32_e32 v2, 0x41800000, v2
	v_mul_f32_e32 v3, 0x41800000, v3
	v_cvt_pk_fp8_f32 v6, v0, v1
	v_mov_b32_e32 v0, v8
	v_cvt_pk_fp8_f32 v0, v2, v3
	v_and_b32_e32 v1, 0xffff, v6
	v_lshl_or_b32 v0, v0, 16, v1
	global_store_dword v[22:23], v0, off offset:112
	s_and_saveexec_b64 s[14:15], s[84:85]
	s_cbranch_execz .LBB0_327
	v_log_f32_e32 v6, v26
	v_readlane_b32 s16, v242, 6
	v_readlane_b32 s17, v242, 7
	v_lshlrev_b32_e32 v2, 2, v222
	v_mov_b32_e32 v3, v8
	v_lshl_add_u64 v[0:1], v[4:5], 4, s[16:17]
	v_add_f32_e32 v4, v25, v6
	v_lshl_add_u64 v[0:1], v[0:1], 0, v[2:3]
	global_store_dword v[0:1], v4, off

; __global__ void __launch_bounds__(512, 2) hybrid_fwd(Args a) {
	.amdhsa_kernel _Z10hybrid_fwd4Args
		.amdhsa_group_segment_fixed_size 0
		.amdhsa_private_segment_fixed_size 0
		.amdhsa_kernarg_size 720
		.amdhsa_user_sgpr_count 2
		.amdhsa_user_sgpr_dispatch_ptr 0
		.amdhsa_user_sgpr_queue_ptr 0
		.amdhsa_user_sgpr_kernarg_segment_ptr 1
		.amdhsa_user_sgpr_dispatch_id 0
		.amdhsa_user_sgpr_kernarg_preload_length 0
		.amdhsa_user_sgpr_kernarg_preload_offset 0
		.amdhsa_user_sgpr_private_segment_size 0
		.amdhsa_uses_dynamic_stack 0
		.amdhsa_enable_private_segment 0
		.amdhsa_system_sgpr_workgroup_id_x 1
		.amdhsa_system_sgpr_workgroup_id_y 0
		.amdhsa_system_sgpr_workgroup_id_z 0
		.amdhsa_system_sgpr_workgroup_info 0
		.amdhsa_system_vgpr_workitem_id 2
		.amdhsa_next_free_vgpr 256
		.amdhsa_next_free_sgpr 102
		.amdhsa_accum_offset 256
		.amdhsa_reserve_vcc 1
		.amdhsa_float_round_mode_32 0
		.amdhsa_float_round_mode_16_64 0
		.amdhsa_float_denorm_mode_32 3
		.amdhsa_float_denorm_mode_16_64 3
		.amdhsa_dx10_clamp 1
		.amdhsa_ieee_mode 1
		.amdhsa_fp16_overflow 0
		.amdhsa_tg_split 0
		.amdhsa_exception_fp_ieee_invalid_op 0
		.amdhsa_exception_fp_denorm_src 0
		.amdhsa_exception_fp_ieee_div_zero 0
		.amdhsa_exception_fp_ieee_overflow 0
		.amdhsa_exception_fp_ieee_underflow 0
		.amdhsa_exception_fp_ieee_inexact 0
		.amdhsa_exception_int_div_zero 0
	.end_amdhsa_kernel

; __global__ void __launch_bounds__(512, 2) hybrid_fwd(Args a) {
amdhsa.kernels:
  - .agpr_count:     0
    .args:
      - .offset:         0
        .size:           464
        .value_kind:     by_value
      - .offset:         464
        .size:           4
        .value_kind:     hidden_block_count_x
      - .offset:         468
        .size:           4
        .value_kind:     hidden_block_count_y
      - .offset:         472
        .size:           4
        .value_kind:     hidden_block_count_z
      - .offset:         476
        .size:           2
        .value_kind:     hidden_group_size_x
      - .offset:         478
        .size:           2
        .value_kind:     hidden_group_size_y
      - .offset:         480
        .size:           2
        .value_kind:     hidden_group_size_z
      - .offset:         482
        .size:           2
        .value_kind:     hidden_remainder_x
      - .offset:         484
        .size:           2
        .value_kind:     hidden_remainder_y
      - .offset:         486
        .size:           2
        .value_kind:     hidden_remainder_z
      - .offset:         504
        .size:           8
        .value_kind:     hidden_global_offset_x
      - .offset:         512
        .size:           8
        .value_kind:     hidden_global_offset_y
      - .offset:         520
        .size:           8
        .value_kind:     hidden_global_offset_z
      - .offset:         528
        .size:           2
        .value_kind:     hidden_grid_dims
      - .offset:         552
        .size:           8
        .value_kind:     hidden_multigrid_sync_arg
      - .offset:         584
        .size:           4
        .value_kind:     hidden_dynamic_lds_size
    .group_segment_fixed_size: 0
    .kernarg_segment_align: 8
    .kernarg_segment_size: 720
    .language:       OpenCL C
    .language_version:
      - 2
      - 0
    .max_flat_workgroup_size: 512
    .name:           _Z10hybrid_fwd4Args
    .private_segment_fixed_size: 0
    .sgpr_count:     108
    .sgpr_spill_count: 36
    .symbol:         _Z10hybrid_fwd4Args.kd
    .uniform_work_group_size: 1
    .uses_dynamic_stack: false
    .vgpr_count:     256
    .vgpr_spill_count: 0
    .wavefront_size: 64
